# first grid seam: cooperative-groups grid.sync replaced by a plain device-scope counter barrier (release wbl2 + atomic arrive + sc1 poll + acquire inv) on a spare zeroed word of the barrier area; rest
# baseline (speedup 1.0000x reference)
; #define LAS __attribute__((address_space(3)))
; __device__ __forceinline__ void fast_grid_barrier(unsigned* bar, unsigned epoch, volatile LAS unsigned* bst) {
;     __syncthreads();
;     if (threadIdx.x == 0) {
;         const unsigned xcc = bst[0], nx = bst[1], nxcd = bst[2];
;         const unsigned old = __hip_atomic_fetch_add(bar + 64u * (1u + xcc), 1u, __ATOMIC_RELAXED, __HIP_MEMORY_SCOPE_AGENT);
;         if (old + 1u == epoch * nx) { __builtin_amdgcn_fence(__ATOMIC_RELEASE, "agent"); __hip_atomic_fetch_add(bar, 1u, __ATOMIC_RELAXED, __HIP_MEMORY_SCOPE_AGENT); }
;         while (__hip_atomic_load(bar, __ATOMIC_RELAXED, __HIP_MEMORY_SCOPE_AGENT) < epoch * nxcd) { }
;         __builtin_amdgcn_fence(__ATOMIC_ACQUIRE, "agent");
;     }
;     __syncthreads();
; }
; __global__ void __launch_bounds__(512, 2) mega(Args a) {
;     ...
;         if (step > a.lo) {
;             if (step == a.lo + 1) {
;                 grid.sync();
.LBB0_19:
	s_and_b64 vcc, exec, s[4:5]
	s_cbranch_vccz .LBB0_33
	s_barrier
	s_mov_b64 s[4:5], exec
	v_readlane_b32 s6, v254, 45
	v_readlane_b32 s7, v254, 46
	s_and_b64 s[6:7], s[4:5], s[6:7]
	s_mov_b64 exec, s[6:7]
	s_cbranch_execz .LBB0_30
	v_readlane_b32 s6, v254, 1
	v_readlane_b32 s7, v254, 2
	buffer_wbl2 sc1
	s_waitcnt vmcnt(0)
	s_nop 3
	s_load_dword s2, s[6:7], 0xa0
	s_waitcnt lgkmcnt(0)
	s_add_u32 s6, s18, 0x3000
	s_addc_u32 s7, s19, 0
	v_mov_b32_e32 v2, 1
	v_mov_b32_e32 v0, s2
	global_atomic_add v1, v2, s[6:7]
.Lfirst_spin:
	s_sleep 1
	global_load_dword v2, v1, s[6:7] sc1
	s_waitcnt vmcnt(0)
	v_cmp_lt_u32_e32 vcc, v2, v0
	s_cbranch_vccnz .Lfirst_spin
